# E69: E66 plus the diff first-tile-copy exp2 slices re-spaced three per gap behind QK MFMAs c/d/e (E62's change)
# speedup vs baseline: 1.0102x; 1.0102x over previous
; #define SBAR() __builtin_amdgcn_sched_barrier(0)
; template <int D0> __device__ __forceinline__ void pv_one_mi(f32x16& od, int vb, bf16x8 pa0, bf16x8 pa1, bf16x8 pa2, bf16x8 pa3, f32x16& q0) {
;   const s16x4 l0 = tr_read<v_rd_off(D0, 0, 0)>(vb), h0 = tr_read<v_rd_off(D0, 0, 1)>(vb), l1 = tr_read<v_rd_off(D0, 1, 0)>(vb), h1 = tr_read<v_rd_off(D0, 1, 1)>(vb);
;   const s16x4 l2 = tr_read<v_rd_off(D0, 2, 0)>(vb), h2 = tr_read<v_rd_off(D0, 2, 1)>(vb), l3 = tr_read<v_rd_off(D0, 3, 0)>(vb), h3 = tr_read<v_rd_off(D0, 3, 1)>(vb);
;   asm volatile("s_waitcnt lgkmcnt(0)" ::: "memory"); SBAR();
;     ...
;   od = __builtin_amdgcn_mfma_f32_32x32x16_bf16(pa0, PK(l0, h0), od, 0, 0, 0);
;   od = __builtin_amdgcn_mfma_f32_32x32x16_bf16(pa1, PK(l1, h1), od, 0, 0, 0);
;   od = __builtin_amdgcn_mfma_f32_32x32x16_bf16(pa2, PK(l2, h2), od, 0, 0, 0);
;   od = __builtin_amdgcn_mfma_f32_32x32x16_bf16(pa3, PK(l3, h3), od, 0, 0, 0);
;     ...
; #pragma unroll
;   for (int r = 4 * D0; r < 4 * D0 + 4; ++r) q0[r] = __builtin_amdgcn_exp2f(q0[r]);
; }
; __device__ __forceinline__ void pv_mi(f32x16* o, int vb, bf16x8 pa0, bf16x8 pa1, bf16x8 pa2, bf16x8 pa3, f32x16& q0) {
;   pv_one_mi<0>(o[0], vb, pa0, pa1, pa2, pa3, q0); pv_one_mi<1>(o[1], vb, pa0, pa1, pa2, pa3, q0);
;   pv_one_mi<2>(o[2], vb, pa0, pa1, pa2, pa3, q0); pv_one_mi<3>(o[3], vb, pa0, pa1, pa2, pa3, q0);
; }
.LBB0_1288:
	v_cvt_pk_bf16_f32 v232, v175, v176
	v_cvt_pk_bf16_f32 v233, v177, v178
	v_cvt_pk_bf16_f32 v234, v179, v181
	v_cvt_pk_bf16_f32 v235, v183, v185
	v_cvt_pk_bf16_f32 v236, v180, v182
	v_cvt_pk_bf16_f32 v237, v184, v227
	v_cvt_pk_bf16_f32 v238, v228, v229
	v_cvt_pk_bf16_f32 v239, v230, v174
	v_cvt_pk_bf16_f32 v228, v96, v97
	v_cvt_pk_bf16_f32 v229, v202, v99
	v_cvt_pk_bf16_f32 v230, v100, v101
	v_cvt_pk_bf16_f32 v231, v102, v103
	v_cvt_pk_bf16_f32 v96, v98, v104
	v_cvt_pk_bf16_f32 v97, v105, v106
	v_cvt_pk_bf16_f32 v98, v107, v108
	v_cvt_pk_bf16_f32 v99, v109, v110
	s_add_i32 s8, s13, 0xfffe8000
	s_add_i32 s9, s12, 0xfffe0000
	s_mov_b32 s38, s30
	s_mov_b32 s39, s31
	s_add_i32 s10, s13, 0xffff0000
	buffer_load_dwordx4 v[174:177], v216, s[28:31], s8 offen
	buffer_load_dwordx4 v[178:181], v216, s[28:31], s10 offen
	buffer_load_dwordx4 v[182:185], v217, s[36:39], s9 offen
	s_lshl_b32 s10, s58, 14
	v_add_u32_e32 v215, s10, v214
	ds_read_b64_tr_b16 v[100:101], v215 offset:0
	ds_read_b64_tr_b16 v[102:103], v215 offset:0x800
	ds_read_b64_tr_b16 v[104:105], v215 offset:0x1000
	ds_read_b64_tr_b16 v[106:107], v215 offset:0x1800
	ds_read_b64_tr_b16 v[108:109], v215 offset:0x2000
	ds_read_b64_tr_b16 v[110:111], v215 offset:0x2800
	ds_read_b64_tr_b16 v[240:241], v215 offset:0x3000
	ds_read_b64_tr_b16 v[242:243], v215 offset:0x3800
	s_waitcnt lgkmcnt(6)
	s_nop 0
	v_mfma_f32_32x32x16_bf16 v[0:15], v[232:235], v[100:103], v[0:15]
	ds_read_b64_tr_b16 v[100:101], v215 offset:0x200
	ds_read_b64_tr_b16 v[102:103], v215 offset:0xa00
	s_waitcnt lgkmcnt(6)
	v_mfma_f32_32x32x16_bf16 v[0:15], v[236:239], v[104:107], v[0:15]
	ds_read_b64_tr_b16 v[104:105], v215 offset:0x1200
	ds_read_b64_tr_b16 v[106:107], v215 offset:0x1a00
	s_waitcnt lgkmcnt(6)
	v_mfma_f32_32x32x16_bf16 v[0:15], v[228:231], v[108:111], v[0:15]
	ds_read_b64_tr_b16 v[108:109], v215 offset:0x2200
	ds_read_b64_tr_b16 v[110:111], v215 offset:0x2a00
	s_waitcnt lgkmcnt(6)
	v_mfma_f32_32x32x16_bf16 v[0:15], v[96:99], v[240:243], v[0:15]
	ds_read_b64_tr_b16 v[240:241], v215 offset:0x3200
	ds_read_b64_tr_b16 v[242:243], v215 offset:0x3a00
	s_waitcnt lgkmcnt(6)
	v_mfma_f32_32x32x16_bf16 v[48:63], v[232:235], v[100:103], v[48:63]
	ds_read_b64_tr_b16 v[100:101], v215 offset:0x400
	ds_read_b64_tr_b16 v[102:103], v215 offset:0xc00
	s_waitcnt lgkmcnt(6)
	v_mfma_f32_32x32x16_bf16 v[48:63], v[236:239], v[104:107], v[48:63]
	ds_read_b64_tr_b16 v[104:105], v215 offset:0x1400
	ds_read_b64_tr_b16 v[106:107], v215 offset:0x1c00
	s_waitcnt lgkmcnt(6)
	v_mfma_f32_32x32x16_bf16 v[48:63], v[228:231], v[108:111], v[48:63]
	ds_read_b64_tr_b16 v[108:109], v215 offset:0x2400
	ds_read_b64_tr_b16 v[110:111], v215 offset:0x2c00
	s_waitcnt lgkmcnt(6)
	v_mfma_f32_32x32x16_bf16 v[48:63], v[96:99], v[240:243], v[48:63]
	ds_read_b64_tr_b16 v[240:241], v215 offset:0x3400
	ds_read_b64_tr_b16 v[242:243], v215 offset:0x3c00
	s_waitcnt lgkmcnt(6)
	v_mfma_f32_32x32x16_bf16 v[32:47], v[232:235], v[100:103], v[32:47]
	ds_read_b64_tr_b16 v[100:101], v215 offset:0x600
	ds_read_b64_tr_b16 v[102:103], v215 offset:0xe00
	s_waitcnt lgkmcnt(6)
	v_mfma_f32_32x32x16_bf16 v[32:47], v[236:239], v[104:107], v[32:47]
	ds_read_b64_tr_b16 v[104:105], v215 offset:0x1600
	ds_read_b64_tr_b16 v[106:107], v215 offset:0x1e00
	s_waitcnt lgkmcnt(6)
	v_mfma_f32_32x32x16_bf16 v[32:47], v[228:231], v[108:111], v[32:47]
	ds_read_b64_tr_b16 v[108:109], v215 offset:0x2600
	ds_read_b64_tr_b16 v[110:111], v215 offset:0x2e00
	s_waitcnt lgkmcnt(6)
	v_mfma_f32_32x32x16_bf16 v[32:47], v[96:99], v[240:243], v[32:47]
	ds_read_b64_tr_b16 v[240:241], v215 offset:0x3600
	ds_read_b64_tr_b16 v[242:243], v215 offset:0x3e00
	s_waitcnt lgkmcnt(6)
	v_mfma_f32_32x32x16_bf16 v[16:31], v[232:235], v[100:103], v[16:31]
	s_waitcnt vmcnt(3)
	s_lshl_b32 s16, s59, 14
	v_add_u32_e32 v100, s16, v218
	s_mul_i32 s11, s59, 0x2400
	s_waitcnt vmcnt(5)
	ds_write_b128 v100, v[162:165]
	s_waitcnt vmcnt(4)
	ds_write_b128 v100, v[166:169] offset:8192
	v_add_u32_e32 v100, s11, v219
	v_cmp_gt_f32_e32 vcc, 1.0, v226
	s_waitcnt lgkmcnt(6)
	v_mfma_f32_32x32x16_bf16 v[16:31], v[236:239], v[104:107], v[16:31]
	s_waitcnt vmcnt(3)
	ds_write_b128 v100, v[170:173] offset:49152
	s_waitcnt lgkmcnt(5)
	v_mfma_f32_32x32x16_bf16 v[16:31], v[228:231], v[108:111], v[16:31]
	s_waitcnt lgkmcnt(3)
	v_mfma_f32_32x32x16_bf16 v[16:31], v[96:99], v[240:243], v[16:31]
	s_cbranch_vccz .LBB0_1292
	s_and_saveexec_b64 s[8:9], s[6:7]
	ds_write_b32 v199, v226 offset:128
	s_or_b64 exec, exec, s[8:9]
	s_waitcnt lgkmcnt(0)
	v_add_u32_e32 v108, v191, v198
	ds_read_b128 v[96:99], v108 offset:224
	ds_read_b128 v[100:103], v108 offset:192
	ds_read_b128 v[104:107], v108 offset:160
	ds_read_b128 v[108:111], v108 offset:128
	s_waitcnt lgkmcnt(3)
	v_pk_mul_f32 v[12:13], v[12:13], v[96:97]
	s_waitcnt lgkmcnt(2)
	v_pk_mul_f32 v[8:9], v[8:9], v[100:101]
	s_waitcnt lgkmcnt(1)
	v_pk_mul_f32 v[4:5], v[4:5], v[104:105]
	v_pk_mul_f32 v[14:15], v[14:15], v[98:99]
	v_pk_mul_f32 v[10:11], v[10:11], v[102:103]
	v_pk_mul_f32 v[6:7], v[6:7], v[106:107]
	s_waitcnt lgkmcnt(0)
	v_pk_mul_f32 v[2:3], v[2:3], v[110:111]
	v_pk_mul_f32 v[0:1], v[0:1], v[108:109]
	v_pk_mul_f32 v[60:61], v[60:61], v[96:97]
	v_pk_mul_f32 v[56:57], v[56:57], v[100:101]
	v_pk_mul_f32 v[52:53], v[52:53], v[104:105]
	v_pk_mul_f32 v[62:63], v[62:63], v[98:99]
	v_pk_mul_f32 v[58:59], v[58:59], v[102:103]
	v_pk_mul_f32 v[54:55], v[54:55], v[106:107]
	v_pk_mul_f32 v[50:51], v[50:51], v[110:111]
	v_pk_mul_f32 v[48:49], v[48:49], v[108:109]
	v_pk_mul_f32 v[44:45], v[44:45], v[96:97]
	v_pk_mul_f32 v[40:41], v[40:41], v[100:101]
	v_pk_mul_f32 v[36:37], v[36:37], v[104:105]
	v_pk_mul_f32 v[46:47], v[46:47], v[98:99]
	v_pk_mul_f32 v[42:43], v[42:43], v[102:103]
	v_pk_mul_f32 v[38:39], v[38:39], v[106:107]
	v_pk_mul_f32 v[34:35], v[34:35], v[110:111]
	v_pk_mul_f32 v[32:33], v[32:33], v[108:109]
	v_pk_mul_f32 v[28:29], v[28:29], v[96:97]
	v_pk_mul_f32 v[24:25], v[24:25], v[100:101]
	v_pk_mul_f32 v[20:21], v[20:21], v[104:105]
	v_pk_mul_f32 v[30:31], v[30:31], v[98:99]
	v_pk_mul_f32 v[26:27], v[26:27], v[102:103]
	v_pk_mul_f32 v[22:23], v[22:23], v[106:107]
	v_pk_mul_f32 v[18:19], v[18:19], v[110:111]
	v_pk_mul_f32 v[16:17], v[16:17], v[108:109]
